# attention item prologue: rel-pos-bias table loads no longer wait (vmcnt 0) in front of the Q / K / V chunk loads; they are consumed after the chunk-0 wait ladder
# baseline (speedup 1.0000x reference)
.LBB0_461:
	s_or_b64 exec, exec, s[4:5]
	v_and_b32_e32 v184, 7, v2
	s_and_saveexec_b64 s[6:7], s[0:1]
	s_cbranch_execz .LBB0_464
	v_mul_u32_u24_e32 v2, 0x1d1, v184
	v_readlane_b32 s8, v245, 0
	v_add_lshl_u32 v2, v130, v2, 2
	v_mov_b32_e32 v3, v133
	v_readlane_b32 s9, v245, 1
	v_mov_b32_e32 v4, v175
	v_mov_b32_e32 v5, v174
	v_lshl_add_u64 v[2:3], s[8:9], 0, v[2:3]
	s_mov_b64 s[8:9], 0
	v_readlane_b32 s10, v245, 2
	v_readlane_b32 s11, v245, 3
	v_readlane_b32 s12, v245, 4
	v_readlane_b32 s13, v245, 5
	v_readlane_b32 s14, v245, 6
	v_readlane_b32 s15, v245, 7
	v_readlane_b32 s16, v245, 8
	v_readlane_b32 s17, v245, 9
	v_readlane_b32 s18, v245, 10
	v_readlane_b32 s19, v245, 11
	v_readlane_b32 s20, v245, 12
	v_readlane_b32 s21, v245, 13
	v_readlane_b32 s22, v245, 14
	v_readlane_b32 s23, v245, 15
	global_load_dword v226, v[2:3], off
	s_movk_i32 s3, 0xd1
	v_cmp_gt_u32_e64 s[4:5], s3, v130
	s_and_saveexec_b64 s[8:9], s[4:5]
	global_load_dword v227, v[2:3], off offset:1024
	s_mov_b64 exec, s[8:9]

.LBB0_470:
	s_andn2_saveexec_b64 s[4:5], s[4:5]
	v_lshlrev_b64 v[60:61], 16, v[34:35]
	v_lshl_add_u64 v[62:63], s[80:81], 0, v[60:61]
	s_mov_b64 s[6:7], 0x2000
	v_lshl_add_u64 v[60:61], s[92:93], 0, v[60:61]
	v_lshl_add_u64 v[36:37], v[62:63], 0, s[6:7]
	v_lshl_add_u64 v[38:39], v[60:61], 0, s[6:7]
	s_or_b64 exec, exec, s[4:5]
	v_lshl_add_u64 v[60:61], v[38:39], 0, v[142:143]
	v_lshl_add_u64 v[60:61], v[60:61], 0, v[138:139]
	v_lshl_add_u64 v[62:63], v[38:39], 0, v[132:133]
	v_lshl_add_u64 v[62:63], v[62:63], 0, v[138:139]
	global_load_dwordx4 v[114:117], v[60:61], off
	global_load_dwordx4 v[118:121], v[62:63], off
	v_lshl_add_u64 v[60:61], v[36:37], 0, v[142:143]
	v_lshl_add_u64 v[60:61], v[60:61], 0, v[138:139]
	v_lshl_add_u64 v[62:63], v[36:37], 0, v[132:133]
	v_lshl_add_u64 v[62:63], v[62:63], 0, v[138:139]
	global_load_dwordx4 v[122:125], v[60:61], off
	global_load_dwordx4 v[126:129], v[62:63], off
	s_waitcnt vmcnt(7)
	ds_write_b128 v176, v[6:9]
	s_waitcnt vmcnt(6)
	ds_write_b128 v177, v[10:13]
	s_waitcnt vmcnt(5)
	ds_write2_b64 v179, v[2:3], v[4:5] offset0:128 offset1:130
	s_waitcnt vmcnt(4)
	ds_write2_b64 v180, v[14:15], v[16:17] offset0:128 offset1:130
	s_and_saveexec_b64 s[98:99], s[0:1]
	s_cbranch_execz .Lrpb_done
	v_mov_b32_e32 v229, 0xd1
	v_cmp_gt_u32_e64 s[100:101], v229, v130
	v_mul_f32_e32 v226, 0x3fb8aa3b, v226
	ds_write_b32 v174, v226
	s_and_b64 exec, exec, s[100:101]
	v_mul_f32_e32 v227, 0x3fb8aa3b, v227
	ds_write_b32 v174, v227 offset:1024
.Lrpb_done:
	s_mov_b64 exec, s[98:99]
	v_mov_b32_e32 v16, v133
	v_mov_b32_e32 v17, v133
	v_mov_b32_e32 v2, v133
	v_mov_b32_e32 v3, v133
	v_mov_b32_e32 v4, v133
	v_mov_b32_e32 v5, v133
	v_mov_b32_e32 v6, v133
	v_mov_b32_e32 v7, v133
	v_mov_b32_e32 v8, v133
	v_mov_b32_e32 v9, v133
	v_mov_b32_e32 v10, v133
	v_mov_b32_e32 v11, v133
	v_mov_b32_e32 v12, v133
	v_mov_b32_e32 v13, v133
	v_mov_b32_e32 v14, v133
	v_mov_b32_e32 v15, v133
	v_mov_b64_e32 v[32:33], v[16:17]
	v_cmp_lt_i32_e32 vcc, 0, v183
	v_mov_b32_e32 v149, 0
	v_mov_b64_e32 v[30:31], v[14:15]
	v_mov_b64_e32 v[28:29], v[12:13]
	v_mov_b64_e32 v[26:27], v[10:11]
	v_mov_b64_e32 v[24:25], v[8:9]
	v_mov_b64_e32 v[22:23], v[6:7]
	v_mov_b64_e32 v[20:21], v[4:5]
	v_mov_b64_e32 v[18:19], v[2:3]
	s_and_saveexec_b64 s[82:83], vcc
	s_cbranch_execz .LBB0_456
	v_lshlrev_b64 v[2:3], 16, v[34:35]
	v_lshl_add_u64 v[156:157], s[80:81], 0, v[2:3]
	v_lshl_add_u64 v[158:159], s[92:93], 0, v[2:3]
	v_sub_u32_e32 v2, v171, v42
	v_lshl_add_u32 v187, v2, 2, v160
	v_sub_u32_e32 v2, v171, v41
	v_and_b32_e32 v3, -16, v2
	s_movk_i32 s3, 0xffe0
	v_cmp_eq_u32_e64 s[6:7], s3, v3
	s_movk_i32 s3, 0xffef
	v_add_u32_e32 v4, 1, v2
	v_cmp_lt_u32_e64 s[38:39], s3, v2
	s_movk_i32 s3, 0xffd0
	v_cmp_gt_u32_e64 s[8:9], 16, v4
	v_add_u32_e32 v4, 33, v2
	v_cmp_eq_u32_e64 s[40:41], s3, v3
	v_add_u32_e32 v3, 17, v2
	v_cmp_gt_u32_e64 s[10:11], 16, v4
	v_add_u32_e32 v4, 2, v2
	v_cmp_gt_u32_e64 s[42:43], 16, v3
	v_add_u32_e32 v3, 49, v2
	v_cmp_gt_u32_e64 s[12:13], 16, v4
	v_add_u32_e32 v4, 34, v2
	v_cmp_gt_u32_e64 s[44:45], 16, v3
	v_add_u32_e32 v3, 18, v2
	v_cmp_gt_u32_e64 s[14:15], 16, v4
	v_add_u32_e32 v4, 3, v2
	v_cmp_gt_u32_e64 s[46:47], 16, v3
	v_add_u32_e32 v3, 50, v2
	v_cmp_gt_u32_e64 s[16:17], 16, v4
	v_add_u32_e32 v4, 35, v2
	v_cmp_gt_u32_e64 s[48:49], 16, v3
	v_add_u32_e32 v3, 19, v2
	v_cmp_gt_u32_e64 s[18:19], 16, v4
	v_add_u32_e32 v4, 8, v2
	v_cmp_gt_u32_e64 s[50:51], 16, v3
	v_add_u32_e32 v3, 51, v2
	v_cmp_gt_u32_e64 s[20:21], 16, v4
	v_add_u32_e32 v4, 40, v2
	v_cmp_gt_u32_e64 s[52:53], 16, v3
	v_add_u32_e32 v3, 24, v2
	v_cmp_gt_u32_e64 s[22:23], 16, v4
	v_add_u32_e32 v4, 9, v2
	v_cmp_gt_u32_e64 s[54:55], 16, v3
	v_add_u32_e32 v3, 56, v2
	v_cmp_gt_u32_e64 s[24:25], 16, v4
	v_add_u32_e32 v4, 41, v2
	v_cmp_gt_u32_e64 s[56:57], 16, v3
	v_add_u32_e32 v3, 25, v2
	v_cmp_gt_u32_e64 s[26:27], 16, v4
	v_add_u32_e32 v4, 10, v2
	v_cmp_gt_u32_e64 s[58:59], 16, v3
	v_add_u32_e32 v3, 57, v2
	v_cmp_gt_u32_e64 s[28:29], 16, v4
	v_add_u32_e32 v4, 42, v2
	v_cmp_gt_u32_e64 s[60:61], 16, v3
	v_add_u32_e32 v3, 26, v2
	v_cmp_gt_u32_e64 s[30:31], 16, v4
	v_add_u32_e32 v4, 11, v2
	v_cmp_gt_u32_e64 s[62:63], 16, v3
	v_add_u32_e32 v3, 58, v2
	v_cmp_gt_u32_e64 s[4:5], 16, v2
	v_cmp_gt_u32_e64 s[34:35], 16, v4
	v_add_u32_e32 v4, 43, v2
	v_cmp_gt_u32_e64 s[64:65], 16, v3
	v_add_u32_e32 v3, 27, v2
	v_add_u32_e32 v2, 59, v2
	v_cmp_gt_u32_e64 s[66:67], 16, v3
	v_cmp_gt_u32_e64 s[68:69], 16, v2
	v_mul_u32_u24_e32 v2, 31, v145
	v_mul_u32_u24_e32 v3, 31, v40
	v_sub_u32_e32 v2, v2, v3
	v_mov_b32_e32 v16, v133
	v_mov_b32_e32 v17, v133
	v_cmp_gt_u32_e64 s[36:37], 16, v4
	v_subrev_u32_e32 v188, 31, v2
	v_mov_b32_e32 v2, v133
	v_mov_b32_e32 v3, v133
	v_mov_b32_e32 v4, v133
	v_mov_b32_e32 v5, v133
	v_mov_b32_e32 v6, v133
	v_mov_b32_e32 v7, v133
	v_mov_b32_e32 v8, v133
	v_mov_b32_e32 v9, v133
	v_mov_b32_e32 v10, v133
	v_mov_b32_e32 v11, v133
	v_mov_b32_e32 v12, v133
	v_mov_b32_e32 v13, v133
	v_mov_b32_e32 v14, v133
	v_mov_b32_e32 v15, v133
	v_mov_b64_e32 v[32:33], v[16:17]
	v_add_u32_e32 v185, -1, v183
	v_mul_hi_u32_u24_e32 v153, 0x6000, v184
	v_mul_u32_u24_e32 v152, 0x6000, v184
	v_mul_hi_u32_u24_e32 v155, 0x180, v184
	v_mul_u32_u24_e32 v154, 0x180, v184
	v_add_u32_e32 v186, 8, v182
	v_add_u32_e32 v189, -8, v145
	s_mov_b32 s3, 0
	v_mov_b32_e32 v190, 0xff800000
	v_mov_b32_e32 v149, 0
	s_mov_b64 s[70:71], 0
	s_xor_b64 s[86:87], s[0:1], -1
	v_mov_b64_e32 v[30:31], v[14:15]
	v_mov_b64_e32 v[28:29], v[12:13]
	v_mov_b64_e32 v[26:27], v[10:11]
	v_mov_b64_e32 v[24:25], v[8:9]
	v_mov_b64_e32 v[22:23], v[6:7]
	v_mov_b64_e32 v[20:21], v[4:5]
	v_mov_b64_e32 v[18:19], v[2:3]
	v_mov_b32_e32 v36, 0
	v_mov_b32_e32 v38, 0
	s_mov_b64 s[72:73], s[86:87]
	s_and_saveexec_b64 s[76:77], s[72:73]
	s_xor_b64 s[72:73], exec, s[76:77]
	s_cbranch_execz .Laddr478_a
	v_add_u32_e32 v34, v36, v145
	v_lshl_add_u32 v34, v34, 6, v181
	v_cndmask_b32_e64 v34, v38, v34, s[0:1]
	v_add_u32_e32 v36, v34, v148
	v_ashrrev_i32_e32 v37, 31, v36
	v_lshl_add_u64 v[34:35], v[152:153], 0, v[36:37]
	v_ashrrev_i32_e32 v36, 6, v36
	v_lshlrev_b64 v[34:35], 7, v[34:35]
	v_ashrrev_i32_e32 v37, 31, v36
	v_lshl_add_u64 v[34:35], s[88:89], 0, v[34:35]
	v_lshl_add_u64 v[36:37], v[154:155], 0, v[36:37]
